# rwkv_post g-matmul: next r-step weight loads prefetched (register rotation)
# baseline (speedup 1.0000x reference)
.LBB0_926:
	s_or_b64 exec, exec, s[10:11]
	v_mov_b32_e32 v54, 0
	s_mov_b32 s9, -4
	s_mov_b32 s10, 16
	s_mov_b32 s11, 0
	v_mov_b32_e32 v55, v54
	v_mov_b32_e32 v52, v54
	v_mov_b32_e32 v53, v54
	v_mov_b32_e32 v48, v54
	v_mov_b32_e32 v49, v54
	v_mov_b32_e32 v44, v54
	v_mov_b32_e32 v45, v54
	v_mov_b32_e32 v40, v54
	v_mov_b32_e32 v41, v54
	v_mov_b32_e32 v36, v54
	v_mov_b32_e32 v37, v54
	v_mov_b32_e32 v30, v54
	v_mov_b32_e32 v31, v54
	v_mov_b32_e32 v26, v54
	v_mov_b32_e32 v27, v54
	v_mov_b32_e32 v22, v54
	v_mov_b32_e32 v23, v54
	v_mov_b32_e32 v18, v54
	v_mov_b32_e32 v19, v54
	v_mov_b32_e32 v14, v54
	v_mov_b32_e32 v15, v54
	v_mov_b32_e32 v10, v54
	v_mov_b32_e32 v11, v54
	v_mov_b32_e32 v8, v54
	v_mov_b32_e32 v9, v54
	v_mov_b32_e32 v4, v54
	v_mov_b32_e32 v5, v54
	v_mov_b32_e32 v2, v54
	v_mov_b32_e32 v3, v54
	v_mov_b32_e32 v0, v54
	v_mov_b32_e32 v1, v54
	v_mov_b32_e32 v64, v54
	v_mov_b32_e32 v65, v54
	v_mov_b32_e32 v62, v54
	v_mov_b32_e32 v63, v54
	v_mov_b32_e32 v60, v54
	v_mov_b32_e32 v61, v54
	v_mov_b32_e32 v58, v54
	v_mov_b32_e32 v59, v54
	v_mov_b32_e32 v56, v54
	v_mov_b32_e32 v57, v54
	v_mov_b32_e32 v50, v54
	v_mov_b32_e32 v51, v54
	v_mov_b32_e32 v46, v54
	v_mov_b32_e32 v47, v54
	v_mov_b32_e32 v42, v54
	v_mov_b32_e32 v43, v54
	v_mov_b32_e32 v38, v54
	v_mov_b32_e32 v39, v54
	v_mov_b32_e32 v34, v54
	v_mov_b32_e32 v35, v54
	v_mov_b32_e32 v28, v54
	v_mov_b32_e32 v29, v54
	v_mov_b32_e32 v24, v54
	v_mov_b32_e32 v25, v54
	v_mov_b32_e32 v20, v54
	v_mov_b32_e32 v21, v54
	v_mov_b32_e32 v16, v54
	v_mov_b32_e32 v17, v54
	v_mov_b32_e32 v12, v54
	v_mov_b32_e32 v13, v54
	v_mov_b32_e32 v6, v54
	v_mov_b32_e32 v7, v54
	s_waitcnt lgkmcnt(0)
	s_barrier
	v_add_u32_e32 v180, s11, v71
	v_mov_b32_e32 v182, v180
	v_ashrrev_i32_e32 v183, 31, v182
	v_lshl_add_u64 v[182:183], v[182:183], 2, s[52:53]
	global_load_dword v172, v[182:183], off
	v_add_u32_e32 v182, 0x600, v180
	v_ashrrev_i32_e32 v183, 31, v182
	v_lshl_add_u64 v[182:183], v[182:183], 2, s[52:53]
	global_load_dword v173, v[182:183], off
	v_add_u32_e32 v182, 0x200, v180
	v_ashrrev_i32_e32 v183, 31, v182
	v_lshl_add_u64 v[182:183], v[182:183], 2, s[52:53]
	global_load_dword v174, v[182:183], off
	v_add_u32_e32 v182, 0x800, v180
	v_ashrrev_i32_e32 v183, 31, v182
	v_lshl_add_u64 v[182:183], v[182:183], 2, s[52:53]
	global_load_dword v175, v[182:183], off
	v_add_u32_e32 v182, 0x400, v180
	v_ashrrev_i32_e32 v183, 31, v182
	v_lshl_add_u64 v[182:183], v[182:183], 2, s[52:53]
	global_load_dword v176, v[182:183], off
	v_add_u32_e32 v182, 0xa00, v180
	v_ashrrev_i32_e32 v183, 31, v182
	v_lshl_add_u64 v[182:183], v[182:183], 2, s[52:53]
	global_load_dword v177, v[182:183], off
	v_add_u32_e32 v182, 0xc00, v180
	v_ashrrev_i32_e32 v183, 31, v182
	v_lshl_add_u64 v[182:183], v[182:183], 2, s[52:53]
	global_load_dword v178, v[182:183], off
	v_add_u32_e32 v182, 0xe00, v180
	v_ashrrev_i32_e32 v183, 31, v182
	v_lshl_add_u64 v[182:183], v[182:183], 2, s[52:53]
	global_load_dword v179, v[182:183], off
.LBB0_927:
	s_add_i32 s9, s9, 4
	v_mov_b32_e32 v67, s10
	ds_read_b128 v[80:83], v67
	ds_read_b128 v[84:87], v67 offset:512
	s_add_i32 s10, s10, 16
	s_addk_i32 s11, 0x1000
	s_cmpk_gt_u32 s9, 0x7b
	s_waitcnt lgkmcnt(0)
	v_mov_b32_e32 v88, v80
	v_mov_b32_e32 v89, v84
	v_mov_b32_e32 v84, v81
	v_mov_b32_e32 v90, v82
	v_mov_b32_e32 v91, v86
	v_mov_b32_e32 v86, v83
	s_waitcnt vmcnt(0)
	v_mov_b32_e32 v32, v172
	v_mov_b32_e32 v72, v173
	v_mov_b32_e32 v68, v174
	v_mov_b32_e32 v70, v175
	v_mov_b32_e32 v66, v176
	v_mov_b32_e32 v76, v177
	v_mov_b32_e32 v74, v178
	v_mov_b32_e32 v78, v179
	s_cbranch_scc1 .Lgmm_nopf
	v_add_u32_e32 v180, s11, v71
	v_mov_b32_e32 v182, v180
	v_ashrrev_i32_e32 v183, 31, v182
	v_lshl_add_u64 v[182:183], v[182:183], 2, s[52:53]
	global_load_dword v172, v[182:183], off
	v_add_u32_e32 v182, 0x600, v180
	v_ashrrev_i32_e32 v183, 31, v182
	v_lshl_add_u64 v[182:183], v[182:183], 2, s[52:53]
	global_load_dword v173, v[182:183], off
	v_add_u32_e32 v182, 0x200, v180
	v_ashrrev_i32_e32 v183, 31, v182
	v_lshl_add_u64 v[182:183], v[182:183], 2, s[52:53]
	global_load_dword v174, v[182:183], off
	v_add_u32_e32 v182, 0x800, v180
	v_ashrrev_i32_e32 v183, 31, v182
	v_lshl_add_u64 v[182:183], v[182:183], 2, s[52:53]
	global_load_dword v175, v[182:183], off
	v_add_u32_e32 v182, 0x400, v180
	v_ashrrev_i32_e32 v183, 31, v182
	v_lshl_add_u64 v[182:183], v[182:183], 2, s[52:53]
	global_load_dword v176, v[182:183], off
	v_add_u32_e32 v182, 0xa00, v180
	v_ashrrev_i32_e32 v183, 31, v182
	v_lshl_add_u64 v[182:183], v[182:183], 2, s[52:53]
	global_load_dword v177, v[182:183], off
	v_add_u32_e32 v182, 0xc00, v180
	v_ashrrev_i32_e32 v183, 31, v182
	v_lshl_add_u64 v[182:183], v[182:183], 2, s[52:53]
	global_load_dword v178, v[182:183], off
	v_add_u32_e32 v182, 0xe00, v180
	v_ashrrev_i32_e32 v183, 31, v182
	v_lshl_add_u64 v[182:183], v[182:183], 2, s[52:53]
	global_load_dword v179, v[182:183], off
.Lgmm_nopf:
	v_pk_mul_f32 v[80:81], v[72:73], v[84:85] op_sel_hi:[0,1]
	v_pk_fma_f32 v[80:81], v[68:69], v[88:89], v[80:81] op_sel_hi:[0,1,1]
	v_pk_mul_f32 v[82:83], v[66:67], v[84:85] op_sel_hi:[0,1]
	v_pk_fma_f32 v[82:83], v[32:33], v[88:89], v[82:83] op_sel_hi:[0,1,1]
	v_pk_fma_f32 v[80:81], v[76:77], v[90:91], v[80:81] op_sel_hi:[0,1,1]
	v_pk_fma_f32 v[82:83], v[70:71], v[90:91], v[82:83] op_sel_hi:[0,1,1]
	v_pk_fma_f32 v[82:83], v[74:75], v[86:87], v[82:83] op_sel_hi:[0,1,1]
	v_pk_add_f32 v[64:65], v[64:65], v[82:83]
	v_pk_fma_f32 v[80:81], v[78:79], v[86:87], v[80:81] op_sel_hi:[0,1,1]
	v_pk_add_f32 v[54:55], v[54:55], v[80:81]
	ds_read_b128 v[80:83], v67 offset:1024
	ds_read_b128 v[84:87], v67 offset:1536
	s_waitcnt lgkmcnt(1)
	v_mov_b32_e32 v88, v80
	s_waitcnt lgkmcnt(0)
	v_mov_b32_e32 v89, v84
	v_mov_b32_e32 v84, v81
	v_pk_mul_f32 v[80:81], v[72:73], v[84:85] op_sel_hi:[0,1]
	v_mov_b32_e32 v90, v82
	v_mov_b32_e32 v91, v86
	v_mov_b32_e32 v86, v83
	v_pk_mul_f32 v[82:83], v[66:67], v[84:85] op_sel_hi:[0,1]
	v_pk_fma_f32 v[80:81], v[68:69], v[88:89], v[80:81] op_sel_hi:[0,1,1]
	v_pk_fma_f32 v[82:83], v[32:33], v[88:89], v[82:83] op_sel_hi:[0,1,1]
	v_pk_fma_f32 v[80:81], v[76:77], v[90:91], v[80:81] op_sel_hi:[0,1,1]
	v_pk_fma_f32 v[82:83], v[70:71], v[90:91], v[82:83] op_sel_hi:[0,1,1]
	v_pk_fma_f32 v[80:81], v[78:79], v[86:87], v[80:81] op_sel_hi:[0,1,1]
	v_pk_fma_f32 v[82:83], v[74:75], v[86:87], v[82:83] op_sel_hi:[0,1,1]
	v_pk_add_f32 v[62:63], v[62:63], v[82:83]
	v_pk_add_f32 v[52:53], v[52:53], v[80:81]
	ds_read_b128 v[80:83], v67 offset:2048
	ds_read_b128 v[84:87], v67 offset:2560
	s_waitcnt lgkmcnt(1)
	v_mov_b32_e32 v88, v80
	s_waitcnt lgkmcnt(0)
	v_mov_b32_e32 v89, v84
	v_mov_b32_e32 v84, v81
	v_pk_mul_f32 v[80:81], v[72:73], v[84:85] op_sel_hi:[0,1]
	v_mov_b32_e32 v90, v82
	v_mov_b32_e32 v91, v86
	v_mov_b32_e32 v86, v83
	v_pk_mul_f32 v[82:83], v[66:67], v[84:85] op_sel_hi:[0,1]
	v_pk_fma_f32 v[80:81], v[68:69], v[88:89], v[80:81] op_sel_hi:[0,1,1]
	v_pk_fma_f32 v[82:83], v[32:33], v[88:89], v[82:83] op_sel_hi:[0,1,1]
	v_pk_fma_f32 v[80:81], v[76:77], v[90:91], v[80:81] op_sel_hi:[0,1,1]
	v_pk_fma_f32 v[82:83], v[70:71], v[90:91], v[82:83] op_sel_hi:[0,1,1]
	v_pk_fma_f32 v[80:81], v[78:79], v[86:87], v[80:81] op_sel_hi:[0,1,1]
	v_pk_fma_f32 v[82:83], v[74:75], v[86:87], v[82:83] op_sel_hi:[0,1,1]
	v_pk_add_f32 v[60:61], v[60:61], v[82:83]
	v_pk_add_f32 v[48:49], v[48:49], v[80:81]
	ds_read_b128 v[80:83], v67 offset:3072
	ds_read_b128 v[84:87], v67 offset:3584
	s_waitcnt lgkmcnt(1)
	v_mov_b32_e32 v88, v80
	s_waitcnt lgkmcnt(0)
	v_mov_b32_e32 v89, v84
	v_mov_b32_e32 v84, v81
	v_pk_mul_f32 v[80:81], v[72:73], v[84:85] op_sel_hi:[0,1]
	v_mov_b32_e32 v90, v82
	v_mov_b32_e32 v91, v86
	v_mov_b32_e32 v86, v83
	v_pk_mul_f32 v[82:83], v[66:67], v[84:85] op_sel_hi:[0,1]
	v_pk_fma_f32 v[80:81], v[68:69], v[88:89], v[80:81] op_sel_hi:[0,1,1]
	v_pk_fma_f32 v[82:83], v[32:33], v[88:89], v[82:83] op_sel_hi:[0,1,1]
	v_pk_fma_f32 v[80:81], v[76:77], v[90:91], v[80:81] op_sel_hi:[0,1,1]
	v_pk_fma_f32 v[82:83], v[70:71], v[90:91], v[82:83] op_sel_hi:[0,1,1]
	v_pk_fma_f32 v[80:81], v[78:79], v[86:87], v[80:81] op_sel_hi:[0,1,1]
	v_pk_fma_f32 v[82:83], v[74:75], v[86:87], v[82:83] op_sel_hi:[0,1,1]
	v_pk_add_f32 v[58:59], v[58:59], v[82:83]
	v_pk_add_f32 v[44:45], v[44:45], v[80:81]
	ds_read_b128 v[80:83], v67 offset:4096
	ds_read_b128 v[84:87], v67 offset:4608
	s_waitcnt lgkmcnt(1)
	v_mov_b32_e32 v88, v80
	s_waitcnt lgkmcnt(0)
	v_mov_b32_e32 v89, v84
	v_mov_b32_e32 v84, v81
	v_pk_mul_f32 v[80:81], v[72:73], v[84:85] op_sel_hi:[0,1]
	v_mov_b32_e32 v90, v82
	v_mov_b32_e32 v91, v86
	v_mov_b32_e32 v86, v83
	v_pk_mul_f32 v[82:83], v[66:67], v[84:85] op_sel_hi:[0,1]
	v_pk_fma_f32 v[80:81], v[68:69], v[88:89], v[80:81] op_sel_hi:[0,1,1]
	v_pk_fma_f32 v[82:83], v[32:33], v[88:89], v[82:83] op_sel_hi:[0,1,1]
	v_pk_fma_f32 v[80:81], v[76:77], v[90:91], v[80:81] op_sel_hi:[0,1,1]
	v_pk_fma_f32 v[82:83], v[70:71], v[90:91], v[82:83] op_sel_hi:[0,1,1]
	v_pk_fma_f32 v[80:81], v[78:79], v[86:87], v[80:81] op_sel_hi:[0,1,1]
	v_pk_fma_f32 v[82:83], v[74:75], v[86:87], v[82:83] op_sel_hi:[0,1,1]
	v_pk_add_f32 v[56:57], v[56:57], v[82:83]
	v_pk_add_f32 v[40:41], v[40:41], v[80:81]
	ds_read_b128 v[80:83], v67 offset:5120
	ds_read_b128 v[84:87], v67 offset:5632
	s_waitcnt lgkmcnt(1)
	v_mov_b32_e32 v88, v80
	s_waitcnt lgkmcnt(0)
	v_mov_b32_e32 v89, v84
	v_mov_b32_e32 v84, v81
	v_pk_mul_f32 v[80:81], v[72:73], v[84:85] op_sel_hi:[0,1]
	v_mov_b32_e32 v90, v82
	v_mov_b32_e32 v91, v86
	v_mov_b32_e32 v86, v83
	v_pk_mul_f32 v[82:83], v[66:67], v[84:85] op_sel_hi:[0,1]
	v_pk_fma_f32 v[80:81], v[68:69], v[88:89], v[80:81] op_sel_hi:[0,1,1]
	v_pk_fma_f32 v[82:83], v[32:33], v[88:89], v[82:83] op_sel_hi:[0,1,1]
	v_pk_fma_f32 v[80:81], v[76:77], v[90:91], v[80:81] op_sel_hi:[0,1,1]
	v_pk_fma_f32 v[82:83], v[70:71], v[90:91], v[82:83] op_sel_hi:[0,1,1]
	v_pk_fma_f32 v[80:81], v[78:79], v[86:87], v[80:81] op_sel_hi:[0,1,1]
	v_pk_fma_f32 v[82:83], v[74:75], v[86:87], v[82:83] op_sel_hi:[0,1,1]
	v_pk_add_f32 v[50:51], v[50:51], v[82:83]
	v_pk_add_f32 v[36:37], v[36:37], v[80:81]
	ds_read_b128 v[80:83], v67 offset:6144
	ds_read_b128 v[84:87], v67 offset:6656
	s_waitcnt lgkmcnt(1)
	v_mov_b32_e32 v88, v80
	s_waitcnt lgkmcnt(0)
	v_mov_b32_e32 v89, v84
	v_mov_b32_e32 v84, v81
	v_pk_mul_f32 v[80:81], v[72:73], v[84:85] op_sel_hi:[0,1]
	v_mov_b32_e32 v90, v82
	v_mov_b32_e32 v91, v86
	v_mov_b32_e32 v86, v83
	v_pk_mul_f32 v[82:83], v[66:67], v[84:85] op_sel_hi:[0,1]
	v_pk_fma_f32 v[80:81], v[68:69], v[88:89], v[80:81] op_sel_hi:[0,1,1]
	v_pk_fma_f32 v[82:83], v[32:33], v[88:89], v[82:83] op_sel_hi:[0,1,1]
	v_pk_fma_f32 v[80:81], v[76:77], v[90:91], v[80:81] op_sel_hi:[0,1,1]
	v_pk_fma_f32 v[82:83], v[70:71], v[90:91], v[82:83] op_sel_hi:[0,1,1]
	v_pk_fma_f32 v[80:81], v[78:79], v[86:87], v[80:81] op_sel_hi:[0,1,1]
	v_pk_fma_f32 v[82:83], v[74:75], v[86:87], v[82:83] op_sel_hi:[0,1,1]
	v_pk_add_f32 v[46:47], v[46:47], v[82:83]
	v_pk_add_f32 v[30:31], v[30:31], v[80:81]
	ds_read_b128 v[80:83], v67 offset:7168
	ds_read_b128 v[84:87], v67 offset:7680
	s_waitcnt lgkmcnt(1)
	v_mov_b32_e32 v88, v80
	s_waitcnt lgkmcnt(0)
	v_mov_b32_e32 v89, v84
	v_mov_b32_e32 v84, v81
	v_pk_mul_f32 v[80:81], v[72:73], v[84:85] op_sel_hi:[0,1]
	v_mov_b32_e32 v90, v82
	v_mov_b32_e32 v91, v86
	v_mov_b32_e32 v86, v83
	v_pk_mul_f32 v[82:83], v[66:67], v[84:85] op_sel_hi:[0,1]
	v_pk_fma_f32 v[80:81], v[68:69], v[88:89], v[80:81] op_sel_hi:[0,1,1]
	v_pk_fma_f32 v[82:83], v[32:33], v[88:89], v[82:83] op_sel_hi:[0,1,1]
	v_pk_fma_f32 v[80:81], v[76:77], v[90:91], v[80:81] op_sel_hi:[0,1,1]
	v_pk_fma_f32 v[82:83], v[70:71], v[90:91], v[82:83] op_sel_hi:[0,1,1]
	v_pk_fma_f32 v[80:81], v[78:79], v[86:87], v[80:81] op_sel_hi:[0,1,1]
	v_pk_fma_f32 v[82:83], v[74:75], v[86:87], v[82:83] op_sel_hi:[0,1,1]
	v_pk_add_f32 v[42:43], v[42:43], v[82:83]
	v_pk_add_f32 v[26:27], v[26:27], v[80:81]
	ds_read_b128 v[80:83], v67 offset:8192
	ds_read_b128 v[84:87], v67 offset:8704
	s_waitcnt lgkmcnt(1)
	v_mov_b32_e32 v88, v80
	s_waitcnt lgkmcnt(0)
	v_mov_b32_e32 v89, v84
	v_mov_b32_e32 v84, v81
	v_pk_mul_f32 v[80:81], v[72:73], v[84:85] op_sel_hi:[0,1]
	v_mov_b32_e32 v90, v82
	v_mov_b32_e32 v91, v86
	v_mov_b32_e32 v86, v83
	v_pk_mul_f32 v[82:83], v[66:67], v[84:85] op_sel_hi:[0,1]
	v_pk_fma_f32 v[80:81], v[68:69], v[88:89], v[80:81] op_sel_hi:[0,1,1]
	v_pk_fma_f32 v[82:83], v[32:33], v[88:89], v[82:83] op_sel_hi:[0,1,1]
	v_pk_fma_f32 v[80:81], v[76:77], v[90:91], v[80:81] op_sel_hi:[0,1,1]
	v_pk_fma_f32 v[82:83], v[70:71], v[90:91], v[82:83] op_sel_hi:[0,1,1]
	v_pk_fma_f32 v[80:81], v[78:79], v[86:87], v[80:81] op_sel_hi:[0,1,1]
	v_pk_fma_f32 v[82:83], v[74:75], v[86:87], v[82:83] op_sel_hi:[0,1,1]
	v_pk_add_f32 v[38:39], v[38:39], v[82:83]
	v_pk_add_f32 v[22:23], v[22:23], v[80:81]
	ds_read_b128 v[80:83], v67 offset:9216
	ds_read_b128 v[84:87], v67 offset:9728
	s_waitcnt lgkmcnt(1)
	v_mov_b32_e32 v88, v80
	s_waitcnt lgkmcnt(0)
	v_mov_b32_e32 v89, v84
	v_mov_b32_e32 v84, v81
	v_pk_mul_f32 v[80:81], v[72:73], v[84:85] op_sel_hi:[0,1]
	v_mov_b32_e32 v90, v82
	v_mov_b32_e32 v91, v86
	v_mov_b32_e32 v86, v83
	v_pk_mul_f32 v[82:83], v[66:67], v[84:85] op_sel_hi:[0,1]
	v_pk_fma_f32 v[80:81], v[68:69], v[88:89], v[80:81] op_sel_hi:[0,1,1]
	v_pk_fma_f32 v[82:83], v[32:33], v[88:89], v[82:83] op_sel_hi:[0,1,1]
	v_pk_fma_f32 v[80:81], v[76:77], v[90:91], v[80:81] op_sel_hi:[0,1,1]
	v_pk_fma_f32 v[82:83], v[70:71], v[90:91], v[82:83] op_sel_hi:[0,1,1]
	v_pk_fma_f32 v[80:81], v[78:79], v[86:87], v[80:81] op_sel_hi:[0,1,1]
	v_pk_fma_f32 v[82:83], v[74:75], v[86:87], v[82:83] op_sel_hi:[0,1,1]
	v_pk_add_f32 v[34:35], v[34:35], v[82:83]
	v_pk_add_f32 v[18:19], v[18:19], v[80:81]
	ds_read_b128 v[80:83], v67 offset:10240
	ds_read_b128 v[84:87], v67 offset:10752
	s_waitcnt lgkmcnt(1)
	v_mov_b32_e32 v88, v80
	s_waitcnt lgkmcnt(0)
	v_mov_b32_e32 v89, v84
	v_mov_b32_e32 v84, v81
	v_pk_mul_f32 v[80:81], v[72:73], v[84:85] op_sel_hi:[0,1]
	v_mov_b32_e32 v90, v82
	v_mov_b32_e32 v91, v86
	v_mov_b32_e32 v86, v83
	v_pk_mul_f32 v[82:83], v[66:67], v[84:85] op_sel_hi:[0,1]
	v_pk_fma_f32 v[80:81], v[68:69], v[88:89], v[80:81] op_sel_hi:[0,1,1]
	v_pk_fma_f32 v[82:83], v[32:33], v[88:89], v[82:83] op_sel_hi:[0,1,1]
	v_pk_fma_f32 v[80:81], v[76:77], v[90:91], v[80:81] op_sel_hi:[0,1,1]
	v_pk_fma_f32 v[82:83], v[70:71], v[90:91], v[82:83] op_sel_hi:[0,1,1]
	v_pk_fma_f32 v[80:81], v[78:79], v[86:87], v[80:81] op_sel_hi:[0,1,1]
	v_pk_fma_f32 v[82:83], v[74:75], v[86:87], v[82:83] op_sel_hi:[0,1,1]
	v_pk_add_f32 v[28:29], v[28:29], v[82:83]
	v_pk_add_f32 v[14:15], v[14:15], v[80:81]
	ds_read_b128 v[80:83], v67 offset:11264
	ds_read_b128 v[84:87], v67 offset:11776
	s_waitcnt lgkmcnt(1)
	v_mov_b32_e32 v88, v80
	s_waitcnt lgkmcnt(0)
	v_mov_b32_e32 v89, v84
	v_mov_b32_e32 v84, v81
	v_pk_mul_f32 v[80:81], v[72:73], v[84:85] op_sel_hi:[0,1]
	v_mov_b32_e32 v90, v82
	v_mov_b32_e32 v91, v86
	v_mov_b32_e32 v86, v83
	v_pk_mul_f32 v[82:83], v[66:67], v[84:85] op_sel_hi:[0,1]
	v_pk_fma_f32 v[80:81], v[68:69], v[88:89], v[80:81] op_sel_hi:[0,1,1]
	v_pk_fma_f32 v[82:83], v[32:33], v[88:89], v[82:83] op_sel_hi:[0,1,1]
	v_pk_fma_f32 v[80:81], v[76:77], v[90:91], v[80:81] op_sel_hi:[0,1,1]
	v_pk_fma_f32 v[82:83], v[70:71], v[90:91], v[82:83] op_sel_hi:[0,1,1]
	v_pk_fma_f32 v[80:81], v[78:79], v[86:87], v[80:81] op_sel_hi:[0,1,1]
	v_pk_fma_f32 v[82:83], v[74:75], v[86:87], v[82:83] op_sel_hi:[0,1,1]
	v_pk_add_f32 v[24:25], v[24:25], v[82:83]
	v_pk_add_f32 v[10:11], v[10:11], v[80:81]
	ds_read_b128 v[80:83], v67 offset:12288
	ds_read_b128 v[84:87], v67 offset:12800
	s_waitcnt lgkmcnt(1)
	v_mov_b32_e32 v88, v80
	s_waitcnt lgkmcnt(0)
	v_mov_b32_e32 v89, v84
	v_mov_b32_e32 v84, v81
	v_pk_mul_f32 v[80:81], v[72:73], v[84:85] op_sel_hi:[0,1]
	v_mov_b32_e32 v90, v82
	v_mov_b32_e32 v91, v86
	v_mov_b32_e32 v86, v83
	v_pk_mul_f32 v[82:83], v[66:67], v[84:85] op_sel_hi:[0,1]
	v_pk_fma_f32 v[80:81], v[68:69], v[88:89], v[80:81] op_sel_hi:[0,1,1]
	v_pk_fma_f32 v[82:83], v[32:33], v[88:89], v[82:83] op_sel_hi:[0,1,1]
	v_pk_fma_f32 v[80:81], v[76:77], v[90:91], v[80:81] op_sel_hi:[0,1,1]
	v_pk_fma_f32 v[82:83], v[70:71], v[90:91], v[82:83] op_sel_hi:[0,1,1]
	v_pk_fma_f32 v[80:81], v[78:79], v[86:87], v[80:81] op_sel_hi:[0,1,1]
	v_pk_fma_f32 v[82:83], v[74:75], v[86:87], v[82:83] op_sel_hi:[0,1,1]
	v_pk_add_f32 v[20:21], v[20:21], v[82:83]
	v_pk_add_f32 v[8:9], v[8:9], v[80:81]
	ds_read_b128 v[80:83], v67 offset:13312
	ds_read_b128 v[84:87], v67 offset:13824
	s_waitcnt lgkmcnt(1)
	v_mov_b32_e32 v88, v80
	s_waitcnt lgkmcnt(0)
	v_mov_b32_e32 v89, v84
	v_mov_b32_e32 v84, v81
	v_pk_mul_f32 v[80:81], v[72:73], v[84:85] op_sel_hi:[0,1]
	v_mov_b32_e32 v90, v82
	v_mov_b32_e32 v91, v86
	v_mov_b32_e32 v86, v83
	v_pk_mul_f32 v[82:83], v[66:67], v[84:85] op_sel_hi:[0,1]
	v_pk_fma_f32 v[80:81], v[68:69], v[88:89], v[80:81] op_sel_hi:[0,1,1]
	v_pk_fma_f32 v[82:83], v[32:33], v[88:89], v[82:83] op_sel_hi:[0,1,1]
	v_pk_fma_f32 v[80:81], v[76:77], v[90:91], v[80:81] op_sel_hi:[0,1,1]
	v_pk_fma_f32 v[82:83], v[70:71], v[90:91], v[82:83] op_sel_hi:[0,1,1]
	v_pk_fma_f32 v[80:81], v[78:79], v[86:87], v[80:81] op_sel_hi:[0,1,1]
	v_pk_fma_f32 v[82:83], v[74:75], v[86:87], v[82:83] op_sel_hi:[0,1,1]
	v_pk_add_f32 v[16:17], v[16:17], v[82:83]
	v_pk_add_f32 v[4:5], v[4:5], v[80:81]
	ds_read_b128 v[80:83], v67 offset:14336
	ds_read_b128 v[84:87], v67 offset:14848
	s_waitcnt lgkmcnt(1)
	v_mov_b32_e32 v88, v80
	s_waitcnt lgkmcnt(0)
	v_mov_b32_e32 v89, v84
	v_mov_b32_e32 v84, v81
	v_pk_mul_f32 v[80:81], v[72:73], v[84:85] op_sel_hi:[0,1]
	v_mov_b32_e32 v90, v82
	v_mov_b32_e32 v91, v86
	v_mov_b32_e32 v86, v83
	v_pk_mul_f32 v[82:83], v[66:67], v[84:85] op_sel_hi:[0,1]
	v_pk_fma_f32 v[80:81], v[68:69], v[88:89], v[80:81] op_sel_hi:[0,1,1]
	v_pk_fma_f32 v[82:83], v[32:33], v[88:89], v[82:83] op_sel_hi:[0,1,1]
	v_pk_fma_f32 v[80:81], v[76:77], v[90:91], v[80:81] op_sel_hi:[0,1,1]
	v_pk_fma_f32 v[82:83], v[70:71], v[90:91], v[82:83] op_sel_hi:[0,1,1]
	v_pk_fma_f32 v[80:81], v[78:79], v[86:87], v[80:81] op_sel_hi:[0,1,1]
	v_pk_fma_f32 v[82:83], v[74:75], v[86:87], v[82:83] op_sel_hi:[0,1,1]
	v_pk_add_f32 v[12:13], v[12:13], v[82:83]
	v_pk_add_f32 v[2:3], v[2:3], v[80:81]
	ds_read_b128 v[80:83], v67 offset:15360
	ds_read_b128 v[84:87], v67 offset:15872
	s_waitcnt lgkmcnt(1)
	v_mov_b32_e32 v88, v80
	s_waitcnt lgkmcnt(0)
	v_mov_b32_e32 v89, v84
	v_mov_b32_e32 v84, v81
	v_pk_mul_f32 v[72:73], v[72:73], v[84:85] op_sel_hi:[0,1]
	v_pk_mul_f32 v[66:67], v[66:67], v[84:85] op_sel_hi:[0,1]
	v_pk_fma_f32 v[68:69], v[68:69], v[88:89], v[72:73] op_sel_hi:[0,1,1]
	v_mov_b32_e32 v72, v82
	v_mov_b32_e32 v73, v86
	v_pk_fma_f32 v[66:67], v[32:33], v[88:89], v[66:67] op_sel_hi:[0,1,1]
	v_pk_fma_f32 v[68:69], v[76:77], v[72:73], v[68:69] op_sel_hi:[0,1,1]
	v_mov_b32_e32 v86, v83
	v_pk_fma_f32 v[66:67], v[70:71], v[72:73], v[66:67] op_sel_hi:[0,1,1]
	v_pk_fma_f32 v[68:69], v[78:79], v[86:87], v[68:69] op_sel_hi:[0,1,1]
	v_pk_fma_f32 v[66:67], v[74:75], v[86:87], v[66:67] op_sel_hi:[0,1,1]
	v_pk_add_f32 v[6:7], v[6:7], v[66:67]
	v_pk_add_f32 v[0:1], v[0:1], v[68:69]
	s_cbranch_scc0 .LBB0_927
	v_lshl_add_u32 v32, v71, 1, 16
	v_cvt_pk_bf16_f32 v10, v10, v33
	ds_write_b16 v32, v10 offset:62464
	v_cvt_pk_bf16_f32 v10, v25, v33
	ds_write_b16 v32, v10 offset:63488
	v_cvt_pk_bf16_f32 v10, v11, v33
	v_add_u32_e32 v66, 0x4000, v32
	ds_write_b16 v32, v10 offset:64512
	v_cvt_pk_bf16_f32 v10, v20, v33
	ds_write_b16 v66, v10 offset:49152
	v_cvt_pk_bf16_f32 v8, v8, v33
	v_add_u32_e32 v10, 0x10400, v32
	ds_write_b16 v10, v8
	v_cvt_pk_bf16_f32 v8, v21, v33
	ds_write_b16 v66, v8 offset:51200
	v_cvt_pk_bf16_f32 v8, v9, v33
	v_add_u32_e32 v9, 0x10c00, v32
	ds_write_b16 v9, v8
	v_cvt_pk_bf16_f32 v8, v16, v33
	ds_write_b16 v66, v8 offset:53248
	v_cvt_pk_bf16_f32 v4, v4, v33
	v_add_u32_e32 v8, 0x11400, v32
	ds_write_b16 v8, v4
	v_cvt_pk_bf16_f32 v4, v17, v33
	ds_write_b16 v66, v4 offset:55296
	v_cvt_pk_bf16_f32 v4, v5, v33
	v_add_u32_e32 v5, 0x11c00, v32
	ds_write_b16 v5, v4
	v_cvt_pk_bf16_f32 v4, v12, v33
	ds_write_b16 v66, v4 offset:57344
	v_cvt_pk_bf16_f32 v2, v2, v33
	v_add_u32_e32 v4, 0x12400, v32
	ds_write_b16 v4, v2
	v_cvt_pk_bf16_f32 v2, v13, v33
	ds_write_b16 v66, v2 offset:59392
	v_cvt_pk_bf16_f32 v2, v3, v33
	v_add_u32_e32 v3, 0x12c00, v32
	ds_write_b16 v3, v2
	v_cvt_pk_bf16_f32 v2, v6, v33
	ds_write_b16 v66, v2 offset:61440
	v_cvt_pk_bf16_f32 v0, v0, v33
	v_add_u32_e32 v2, 0x13400, v32
	v_cvt_pk_bf16_f32 v48, v48, v33
	ds_write_b16 v2, v0
	v_cvt_pk_bf16_f32 v0, v7, v33
	v_cvt_pk_bf16_f32 v54, v54, v33
	v_cvt_pk_bf16_f32 v52, v52, v33
	ds_write_b16 v32, v48 offset:25600
	v_cvt_pk_bf16_f32 v48, v61, v33
	v_cvt_pk_bf16_f32 v44, v44, v33
	v_cvt_pk_bf16_f32 v40, v40, v33
	v_cvt_pk_bf16_f32 v36, v36, v33
	v_cvt_pk_bf16_f32 v30, v30, v33
	v_cvt_pk_bf16_f32 v26, v26, v33
	v_cvt_pk_bf16_f32 v22, v22, v33
	v_cvt_pk_bf16_f32 v18, v18, v33
	v_cvt_pk_bf16_f32 v14, v14, v33
	ds_write_b16 v66, v0 offset:63488
	v_cvt_pk_bf16_f32 v0, v1, v33
	v_add_u32_e32 v1, 0x13c00, v32
	ds_write_b16 v32, v54 offset:17408
	v_cvt_pk_bf16_f32 v54, v65, v33
	ds_write_b16 v32, v52 offset:21504
	v_cvt_pk_bf16_f32 v52, v63, v33
	ds_write_b16 v32, v48 offset:26624
	v_cvt_pk_bf16_f32 v48, v49, v33
	ds_write_b16 v32, v44 offset:29696
	v_cvt_pk_bf16_f32 v44, v59, v33
	ds_write_b16 v32, v40 offset:33792
	v_cvt_pk_bf16_f32 v40, v57, v33
	ds_write_b16 v32, v36 offset:37888
	v_cvt_pk_bf16_f32 v36, v51, v33
	ds_write_b16 v32, v30 offset:41984
	v_cvt_pk_bf16_f32 v30, v47, v33
	ds_write_b16 v32, v26 offset:46080
	v_cvt_pk_bf16_f32 v26, v43, v33
	ds_write_b16 v32, v22 offset:50176
	v_cvt_pk_bf16_f32 v22, v39, v33
	ds_write_b16 v32, v18 offset:54272
	v_cvt_pk_bf16_f32 v18, v35, v33
	ds_write_b16 v32, v14 offset:58368
	v_cvt_pk_bf16_f32 v14, v29, v33
	ds_write_b16 v1, v0
	v_lshlrev_b32_e32 v0, 3, v71
	ds_write_b16 v32, v54 offset:18432
	v_cvt_pk_bf16_f32 v54, v55, v33
	ds_write_b16 v32, v52 offset:22528
	v_cvt_pk_bf16_f32 v52, v53, v33
	ds_write_b16 v32, v48 offset:27648
	v_cvt_pk_bf16_f32 v48, v58, v33
	ds_write_b16 v32, v44 offset:30720
	v_cvt_pk_bf16_f32 v44, v45, v33
	ds_write_b16 v32, v40 offset:34816
	v_cvt_pk_bf16_f32 v40, v41, v33
	ds_write_b16 v32, v36 offset:38912
	v_cvt_pk_bf16_f32 v36, v37, v33
	ds_write_b16 v32, v30 offset:43008
	v_cvt_pk_bf16_f32 v30, v31, v33
	ds_write_b16 v32, v26 offset:47104
	v_cvt_pk_bf16_f32 v26, v27, v33
	ds_write_b16 v32, v22 offset:51200
	v_cvt_pk_bf16_f32 v22, v23, v33
	ds_write_b16 v32, v18 offset:55296
	v_cvt_pk_bf16_f32 v18, v19, v33
	ds_write_b16 v32, v14 offset:59392
	v_cvt_pk_bf16_f32 v14, v15, v33
	v_and_b32_e32 v58, 0x3f8, v0
	v_cvt_pk_bf16_f32 v64, v64, v33
	ds_write_b16 v32, v64 offset:16384
	ds_write_b16 v32, v54 offset:19456
	v_cvt_pk_bf16_f32 v54, v62, v33
	ds_write_b16 v32, v54 offset:20480
	ds_write_b16 v32, v52 offset:23552
	v_cvt_pk_bf16_f32 v52, v60, v33
	ds_write_b16 v32, v52 offset:24576
	ds_write_b16 v32, v48 offset:28672
	ds_write_b16 v32, v44 offset:31744
	v_cvt_pk_bf16_f32 v44, v56, v33
	ds_write_b16 v32, v44 offset:32768
	ds_write_b16 v32, v40 offset:35840
	v_cvt_pk_bf16_f32 v40, v50, v33
	ds_write_b16 v32, v40 offset:36864
	ds_write_b16 v32, v36 offset:39936
	v_cvt_pk_bf16_f32 v36, v46, v33
	ds_write_b16 v32, v36 offset:40960
	ds_write_b16 v32, v30 offset:44032
	v_cvt_pk_bf16_f32 v30, v42, v33
	ds_write_b16 v32, v30 offset:45056
	ds_write_b16 v32, v26 offset:48128
	v_cvt_pk_bf16_f32 v26, v38, v33
	ds_write_b16 v32, v26 offset:49152
	ds_write_b16 v32, v22 offset:52224
	v_cvt_pk_bf16_f32 v22, v34, v33
	ds_write_b16 v32, v22 offset:53248
	ds_write_b16 v32, v18 offset:56320
	v_cvt_pk_bf16_f32 v18, v28, v33
	ds_write_b16 v32, v18 offset:57344
	ds_write_b16 v32, v14 offset:60416
	v_cvt_pk_bf16_f32 v14, v24, v33
	ds_write_b16 v32, v14 offset:61440
	v_lshlrev_b32_e32 v32, 2, v58
	v_lshl_add_u64 v[16:17], s[42:43], 0, v[32:33]
	s_mov_b64 s[10:11], 0x2000
	v_lshl_add_u64 v[4:5], v[16:17], 0, s[10:11]
	v_add_co_u32_e32 v12, vcc, s75, v16
	s_mov_b64 s[10:11], 0x1000
	s_waitcnt lgkmcnt(0)
	s_barrier
	global_load_dwordx4 v[0:3], v32, s[82:83]
	global_load_dwordx4 v[50:53], v[4:5], off offset:16
	s_nop 0
	global_load_dwordx4 v[4:7], v32, s[80:81] offset:16
	v_addc_co_u32_e32 v13, vcc, 0, v17, vcc
	v_lshl_add_u64 v[16:17], v[16:17], 0, s[10:11]
	global_load_dwordx4 v[54:57], v[12:13], off
	global_load_dwordx4 v[8:11], v32, s[80:81]
	s_nop 0
	global_load_dwordx4 v[12:15], v[12:13], off offset:-4096
	s_nop 0
	global_load_dwordx4 v[16:19], v[16:17], off offset:16
	s_nop 0
	global_load_dwordx4 v[20:23], v32, s[42:43]
	global_load_dwordx4 v[24:27], v32, s[42:43] offset:16
	global_load_dwordx4 v[28:31], v32, s[76:77]
	global_load_dwordx4 v[34:37], v32, s[78:79]
	global_load_dwordx4 v[38:41], v32, s[76:77] offset:16
	global_load_dwordx4 v[42:45], v32, s[78:79] offset:16
	global_load_dwordx4 v[46:49], v32, s[82:83] offset:16
	v_ashrrev_i32_e32 v60, 7, v71
	s_ashr_i32 s9, s8, 31
	v_ashrrev_i32_e32 v61, 31, v60
	s_add_i32 s10, 16, 0x4000
	s_mov_b32 s12, 0
	v_add_u32_e32 v150, s16, v60
	v_lshlrev_b32_e32 v32, 1, v58
	s_waitcnt vmcnt(12)
	v_mov_b32_e32 v64, v50
	s_waitcnt vmcnt(11)
	v_mov_b32_e32 v65, v4
	v_mov_b32_e32 v4, v51
	v_lshl_add_u64 v[50:51], v[60:61], 0, s[8:9]
	v_mov_b32_e32 v62, v52
	v_mov_b32_e32 v63, v6
	v_mov_b32_e32 v6, v53
	v_lshlrev_b64 v[52:53], 12, v[50:51]
	v_mov_b32_e32 v148, v0
	v_lshlrev_b32_e32 v0, 4, v71
	v_lshl_add_u64 v[72:73], s[6:7], 0, v[52:53]
	v_lshlrev_b64 v[52:53], 11, v[50:51]
	v_and_b32_e32 v70, 0x7f0, v0
	v_lshl_add_u64 v[74:75], s[4:5], 0, v[52:53]
	v_lshlrev_b64 v[52:53], 13, v[50:51]
	v_lshl_or_b32 v0, v60, 11, v70
	v_lshl_add_u64 v[76:77], s[0:1], 0, v[52:53]
	v_mov_b64_e32 v[52:53], s[0:1]
	v_add_u32_e32 v149, s10, v0
	v_mad_u64_u32 v[78:79], s[10:11], v50, s96, v[52:53]
	s_waitcnt vmcnt(10)
	v_mov_b32_e32 v66, v56
	s_waitcnt vmcnt(9)
	v_mov_b32_e32 v67, v10
	v_mov_b32_e32 v10, v57
	v_mov_b32_e32 v68, v54
	v_mov_b32_e32 v69, v8
	v_mov_b32_e32 v8, v55
	v_mov_b32_e32 v71, v33
	v_mad_i32_i24 v79, v51, s96, v79
	s_branch .LBB0_930
